# GEMM unit headers: shift/mask tile-index division with s_nop padding that keeps every K loop and later phase at its previous placement mod 64
# baseline (speedup 1.0000x reference)
.LBB0_162:
	s_ashr_i32 s39, s38, 31
	s_lshl_b64 s[40:41], s[38:39], 19
	s_add_u32 s40, s74, s40
	s_addc_u32 s41, s75, s41
	s_and_b64 s[42:43], s[0:1], exec
	s_cselect_b32 s5, s41, s9
	s_cselect_b32 s7, s40, s8
	s_ashr_i32 s37, s36, 31
	s_lshl_b64 s[42:43], s[36:37], 19
	s_add_u32 s42, s16, s42
	s_addc_u32 s43, s17, s43
	s_and_b64 s[46:47], s[0:1], exec
	s_cselect_b32 s37, s43, s45
	s_cselect_b32 s39, s42, s44
	s_add_u32 s8, s8, 0x40080
	s_addc_u32 s9, s9, 0
	s_add_u32 s48, s44, 0x100
	s_addc_u32 s49, s45, 0
	s_mov_b32 s50, -2
	s_nop 0
	s_nop 0
	s_nop 0
	s_nop 0
	s_nop 0
	s_nop 0
	s_nop 0
	s_nop 0
	s_nop 0
	s_nop 0
	s_nop 0
	s_nop 0
	v_mov_b64_e32 v[0:1], 0
	v_mov_b64_e32 v[2:3], 0
	v_mov_b64_e32 v[4:5], 0
	v_mov_b64_e32 v[6:7], 0
	v_mov_b64_e32 v[8:9], 0
	v_mov_b64_e32 v[10:11], 0
	v_mov_b64_e32 v[12:13], 0
	v_mov_b64_e32 v[14:15], 0
	v_mov_b64_e32 v[16:17], 0
	v_mov_b64_e32 v[18:19], 0
	v_mov_b64_e32 v[20:21], 0
	v_mov_b64_e32 v[22:23], 0
	v_mov_b64_e32 v[24:25], 0
	v_mov_b64_e32 v[26:27], 0
	v_mov_b64_e32 v[28:29], 0
	v_mov_b64_e32 v[30:31], 0
	v_mov_b64_e32 v[32:33], 0
	v_mov_b64_e32 v[34:35], 0
	v_mov_b64_e32 v[36:37], 0
	v_mov_b64_e32 v[38:39], 0
	v_mov_b64_e32 v[40:41], 0
	v_mov_b64_e32 v[42:43], 0
	v_mov_b64_e32 v[44:45], 0
	v_mov_b64_e32 v[46:47], 0
	v_mov_b64_e32 v[48:49], 0
	v_mov_b64_e32 v[50:51], 0
	v_mov_b64_e32 v[52:53], 0
	v_mov_b64_e32 v[54:55], 0
	v_mov_b64_e32 v[56:57], 0
	v_mov_b64_e32 v[58:59], 0
	v_mov_b64_e32 v[60:61], 0
	v_mov_b64_e32 v[62:63], 0
	v_mov_b64_e32 v[64:65], 0
	v_mov_b64_e32 v[66:67], 0
	v_mov_b64_e32 v[68:69], 0
	v_mov_b64_e32 v[70:71], 0
	v_mov_b64_e32 v[72:73], 0
	v_mov_b64_e32 v[74:75], 0
	v_mov_b64_e32 v[76:77], 0
	v_mov_b64_e32 v[78:79], 0
	v_mov_b64_e32 v[80:81], 0
	v_mov_b64_e32 v[82:83], 0
	v_mov_b64_e32 v[84:85], 0
	v_mov_b64_e32 v[86:87], 0
	v_mov_b64_e32 v[88:89], 0
	v_mov_b64_e32 v[90:91], 0
	v_mov_b64_e32 v[92:93], 0
	v_mov_b64_e32 v[94:95], 0
	v_mov_b64_e32 v[96:97], 0
	v_mov_b64_e32 v[98:99], 0
	v_mov_b64_e32 v[100:101], 0
	v_mov_b64_e32 v[102:103], 0
	v_mov_b64_e32 v[104:105], 0
	v_mov_b64_e32 v[106:107], 0
	v_mov_b64_e32 v[108:109], 0
	v_mov_b64_e32 v[110:111], 0
	v_mov_b64_e32 v[112:113], 0
	v_mov_b64_e32 v[114:115], 0
	v_mov_b64_e32 v[116:117], 0
	v_mov_b64_e32 v[118:119], 0
	v_mov_b64_e32 v[120:121], 0
	v_mov_b64_e32 v[122:123], 0
	v_mov_b64_e32 v[124:125], 0
	v_mov_b64_e32 v[126:127], 0

.LBB0_639:
	s_ashr_i32 s13, s12, 31
	s_lshl_b64 s[16:17], s[12:13], 19
	s_add_u32 s16, s74, s16
	s_addc_u32 s17, s75, s17
	s_and_b64 s[18:19], s[38:39], exec
	s_cselect_b32 s13, s17, s37
	s_cselect_b32 s67, s16, s36
	s_ashr_i32 s11, s10, 31
	s_lshl_b64 s[18:19], s[10:11], 19
	s_add_u32 s18, s15, s18
	s_addc_u32 s19, s20, s19
	s_and_b64 s[46:47], s[38:39], exec
	s_cselect_b32 s11, s19, s43
	s_cselect_b32 s68, s18, s42
	s_add_u32 s36, s36, 0x40080
	s_addc_u32 s37, s37, 0
	s_add_u32 s69, s42, 0x100
	s_addc_u32 s70, s43, 0
	s_mov_b32 s71, -2
	s_nop 0
	s_nop 0
	s_nop 0
	s_nop 0
	s_nop 0
	s_nop 0
	s_nop 0
	s_nop 0
	s_nop 0
	s_nop 0
	s_nop 0
	s_nop 0
	v_mov_b64_e32 v[0:1], 0
	v_mov_b64_e32 v[2:3], 0
	v_mov_b64_e32 v[4:5], 0
	v_mov_b64_e32 v[6:7], 0
	v_mov_b64_e32 v[8:9], 0
	v_mov_b64_e32 v[10:11], 0
	v_mov_b64_e32 v[12:13], 0
	v_mov_b64_e32 v[14:15], 0
	v_mov_b64_e32 v[16:17], 0
	v_mov_b64_e32 v[18:19], 0
	v_mov_b64_e32 v[20:21], 0
	v_mov_b64_e32 v[22:23], 0
	v_mov_b64_e32 v[24:25], 0
	v_mov_b64_e32 v[26:27], 0
	v_mov_b64_e32 v[28:29], 0
	v_mov_b64_e32 v[30:31], 0
	v_mov_b64_e32 v[32:33], 0
	v_mov_b64_e32 v[34:35], 0
	v_mov_b64_e32 v[36:37], 0
	v_mov_b64_e32 v[38:39], 0
	v_mov_b64_e32 v[40:41], 0
	v_mov_b64_e32 v[42:43], 0
	v_mov_b64_e32 v[44:45], 0
	v_mov_b64_e32 v[46:47], 0
	v_mov_b64_e32 v[48:49], 0
	v_mov_b64_e32 v[50:51], 0
	v_mov_b64_e32 v[52:53], 0
	v_mov_b64_e32 v[54:55], 0
	v_mov_b64_e32 v[56:57], 0
	v_mov_b64_e32 v[58:59], 0
	v_mov_b64_e32 v[60:61], 0
	v_mov_b64_e32 v[62:63], 0
	v_mov_b64_e32 v[64:65], 0
	v_mov_b64_e32 v[66:67], 0
	v_mov_b64_e32 v[68:69], 0
	v_mov_b64_e32 v[70:71], 0
	v_mov_b64_e32 v[72:73], 0
	v_mov_b64_e32 v[74:75], 0
	v_mov_b64_e32 v[76:77], 0
	v_mov_b64_e32 v[78:79], 0
	v_mov_b64_e32 v[80:81], 0
	v_mov_b64_e32 v[82:83], 0
	v_mov_b64_e32 v[84:85], 0
	v_mov_b64_e32 v[86:87], 0
	v_mov_b64_e32 v[88:89], 0
	v_mov_b64_e32 v[90:91], 0
	v_mov_b64_e32 v[92:93], 0
	v_mov_b64_e32 v[94:95], 0
	v_mov_b64_e32 v[96:97], 0
	v_mov_b64_e32 v[98:99], 0
	v_mov_b64_e32 v[100:101], 0
	v_mov_b64_e32 v[102:103], 0
	v_mov_b64_e32 v[104:105], 0
	v_mov_b64_e32 v[106:107], 0
	v_mov_b64_e32 v[108:109], 0
	v_mov_b64_e32 v[110:111], 0
	v_mov_b64_e32 v[112:113], 0
	v_mov_b64_e32 v[114:115], 0
	v_mov_b64_e32 v[116:117], 0
	v_mov_b64_e32 v[118:119], 0
	v_mov_b64_e32 v[120:121], 0
	v_mov_b64_e32 v[122:123], 0
	v_mov_b64_e32 v[124:125], 0
	v_mov_b64_e32 v[126:127], 0

.LBB0_676:
	s_ashr_i32 s13, s12, 31
	s_lshl_b64 s[16:17], s[12:13], 19
	s_add_u32 s16, s15, s16
	s_addc_u32 s17, s20, s17
	s_and_b64 s[18:19], s[38:39], exec
	s_cselect_b32 s13, s17, s37
	s_cselect_b32 s53, s16, s36
	s_ashr_i32 s11, s10, 31
	s_lshl_b64 s[18:19], s[10:11], 19
	s_add_u32 s18, s74, s18
	s_addc_u32 s19, s75, s19
	s_and_b64 s[46:47], s[38:39], exec
	s_cselect_b32 s11, s19, s43
	s_cselect_b32 s64, s18, s42
	s_add_u32 s36, s36, 0x40080
	s_addc_u32 s37, s37, 0
	s_add_u32 s65, s42, 0x100
	s_addc_u32 s66, s43, 0
	s_mov_b32 s67, -2
	s_nop 0
	s_nop 0
	s_nop 0
	s_nop 0
	s_nop 0
	s_nop 0
	s_nop 0
	s_nop 0
	s_nop 0
	s_nop 0
	s_nop 0
	s_nop 0
	v_mov_b64_e32 v[0:1], 0
	v_mov_b64_e32 v[2:3], 0
	v_mov_b64_e32 v[4:5], 0
	v_mov_b64_e32 v[6:7], 0
	v_mov_b64_e32 v[8:9], 0
	v_mov_b64_e32 v[10:11], 0
	v_mov_b64_e32 v[12:13], 0
	v_mov_b64_e32 v[14:15], 0
	v_mov_b64_e32 v[16:17], 0
	v_mov_b64_e32 v[18:19], 0
	v_mov_b64_e32 v[20:21], 0
	v_mov_b64_e32 v[22:23], 0
	v_mov_b64_e32 v[24:25], 0
	v_mov_b64_e32 v[26:27], 0
	v_mov_b64_e32 v[28:29], 0
	v_mov_b64_e32 v[30:31], 0
	v_mov_b64_e32 v[32:33], 0
	v_mov_b64_e32 v[34:35], 0
	v_mov_b64_e32 v[36:37], 0
	v_mov_b64_e32 v[38:39], 0
	v_mov_b64_e32 v[40:41], 0
	v_mov_b64_e32 v[42:43], 0
	v_mov_b64_e32 v[44:45], 0
	v_mov_b64_e32 v[46:47], 0
	v_mov_b64_e32 v[48:49], 0
	v_mov_b64_e32 v[50:51], 0
	v_mov_b64_e32 v[52:53], 0
	v_mov_b64_e32 v[54:55], 0
	v_mov_b64_e32 v[56:57], 0
	v_mov_b64_e32 v[58:59], 0
	v_mov_b64_e32 v[60:61], 0
	v_mov_b64_e32 v[62:63], 0
	v_mov_b64_e32 v[64:65], 0
	v_mov_b64_e32 v[66:67], 0
	v_mov_b64_e32 v[68:69], 0
	v_mov_b64_e32 v[70:71], 0
	v_mov_b64_e32 v[72:73], 0
	v_mov_b64_e32 v[74:75], 0
	v_mov_b64_e32 v[76:77], 0
	v_mov_b64_e32 v[78:79], 0
	v_mov_b64_e32 v[80:81], 0
	v_mov_b64_e32 v[82:83], 0
	v_mov_b64_e32 v[84:85], 0
	v_mov_b64_e32 v[86:87], 0
	v_mov_b64_e32 v[88:89], 0
	v_mov_b64_e32 v[90:91], 0
	v_mov_b64_e32 v[92:93], 0
	v_mov_b64_e32 v[94:95], 0
	v_mov_b64_e32 v[96:97], 0
	v_mov_b64_e32 v[98:99], 0
	v_mov_b64_e32 v[100:101], 0
	v_mov_b64_e32 v[102:103], 0
	v_mov_b64_e32 v[104:105], 0
	v_mov_b64_e32 v[106:107], 0
	v_mov_b64_e32 v[108:109], 0
	v_mov_b64_e32 v[110:111], 0
	v_mov_b64_e32 v[112:113], 0
	v_mov_b64_e32 v[114:115], 0
	v_mov_b64_e32 v[116:117], 0
	v_mov_b64_e32 v[118:119], 0
	v_mov_b64_e32 v[120:121], 0
	v_mov_b64_e32 v[122:123], 0
	v_mov_b64_e32 v[124:125], 0
	v_mov_b64_e32 v[126:127], 0

.LBB0_884:
	s_ashr_i32 s17, s16, 31
	s_lshl_b64 s[18:19], s[16:17], 19
	s_add_u32 s18, s28, s18
	s_addc_u32 s19, s29, s19
	s_and_b64 s[24:25], s[42:43], exec
	s_cselect_b32 s17, s19, s31
	s_cselect_b32 s27, s18, s30
	s_ashr_i32 s13, s12, 31
	s_lshl_b64 s[24:25], s[12:13], 19
	s_add_u32 s24, s60, s24
	s_addc_u32 s25, s61, s25
	s_and_b64 s[36:37], s[42:43], exec
	s_cselect_b32 s13, s25, s35
	s_cselect_b32 s50, s24, s34
	s_add_u32 s30, s30, 0x40080
	s_addc_u32 s31, s31, 0
	s_add_u32 s51, s34, 0x100
	s_addc_u32 s52, s35, 0
	s_mov_b32 s53, -2
	s_waitcnt lgkmcnt(0)
	s_nop 0
	s_nop 0
	s_nop 0
	s_nop 0
	s_nop 0
	s_nop 0
	s_nop 0
	s_nop 0
	s_nop 0
	s_nop 0
	s_nop 0
	s_nop 0
	v_mov_b64_e32 v[0:1], 0
	v_mov_b64_e32 v[2:3], 0
	v_mov_b64_e32 v[4:5], 0
	v_mov_b64_e32 v[6:7], 0
	v_mov_b64_e32 v[8:9], 0
	v_mov_b64_e32 v[10:11], 0
	v_mov_b64_e32 v[12:13], 0
	v_mov_b64_e32 v[14:15], 0
	v_mov_b64_e32 v[16:17], 0
	v_mov_b64_e32 v[18:19], 0
	v_mov_b64_e32 v[20:21], 0
	v_mov_b64_e32 v[22:23], 0
	v_mov_b64_e32 v[24:25], 0
	v_mov_b64_e32 v[26:27], 0
	v_mov_b64_e32 v[28:29], 0
	v_mov_b64_e32 v[30:31], 0
	v_mov_b64_e32 v[32:33], 0
	v_mov_b64_e32 v[34:35], 0
	v_mov_b64_e32 v[36:37], 0
	v_mov_b64_e32 v[38:39], 0
	v_mov_b64_e32 v[40:41], 0
	v_mov_b64_e32 v[42:43], 0
	v_mov_b64_e32 v[44:45], 0
	v_mov_b64_e32 v[46:47], 0
	v_mov_b64_e32 v[48:49], 0
	v_mov_b64_e32 v[50:51], 0
	v_mov_b64_e32 v[52:53], 0
	v_mov_b64_e32 v[54:55], 0
	v_mov_b64_e32 v[56:57], 0
	v_mov_b64_e32 v[58:59], 0
	v_mov_b64_e32 v[60:61], 0
	v_mov_b64_e32 v[62:63], 0
	v_mov_b64_e32 v[64:65], 0
	v_mov_b64_e32 v[66:67], 0
	v_mov_b64_e32 v[68:69], 0
	v_mov_b64_e32 v[70:71], 0
	v_mov_b64_e32 v[72:73], 0
	v_mov_b64_e32 v[74:75], 0
	v_mov_b64_e32 v[76:77], 0
	v_mov_b64_e32 v[78:79], 0
	v_mov_b64_e32 v[80:81], 0
	v_mov_b64_e32 v[82:83], 0
	v_mov_b64_e32 v[84:85], 0
	v_mov_b64_e32 v[86:87], 0
	v_mov_b64_e32 v[88:89], 0
	v_mov_b64_e32 v[90:91], 0
	v_mov_b64_e32 v[92:93], 0
	v_mov_b64_e32 v[94:95], 0
	v_mov_b64_e32 v[96:97], 0
	v_mov_b64_e32 v[98:99], 0
	v_mov_b64_e32 v[100:101], 0
	v_mov_b64_e32 v[102:103], 0
	v_mov_b64_e32 v[104:105], 0
	v_mov_b64_e32 v[106:107], 0
	v_mov_b64_e32 v[108:109], 0
	v_mov_b64_e32 v[110:111], 0
	v_mov_b64_e32 v[112:113], 0
	v_mov_b64_e32 v[114:115], 0
	v_mov_b64_e32 v[116:117], 0
	v_mov_b64_e32 v[118:119], 0
	v_mov_b64_e32 v[120:121], 0
	v_mov_b64_e32 v[122:123], 0
	v_mov_b64_e32 v[124:125], 0
	v_mov_b64_e32 v[126:127], 0

.LBB0_973:
	s_ashr_i32 s17, s16, 31
	s_lshl_b64 s[18:19], s[16:17], 19
	s_add_u32 s18, s82, s18
	s_addc_u32 s19, s83, s19
	s_and_b64 s[20:21], s[40:41], exec
	s_cselect_b32 s17, s19, s27
	s_cselect_b32 s47, s18, s26
	s_ashr_i32 s13, s12, 31
	s_lshl_b64 s[20:21], s[12:13], 19
	s_add_u32 s20, s58, s20
	s_addc_u32 s21, s59, s21
	s_and_b64 s[30:31], s[40:41], exec
	s_cselect_b32 s13, s21, s29
	s_cselect_b32 s48, s20, s28
	s_add_u32 s26, s26, 0x40080
	s_addc_u32 s27, s27, 0
	s_add_u32 s49, s28, 0x100
	s_addc_u32 s50, s29, 0
	s_mov_b32 s51, -2
	s_nop 0
	s_nop 0
	s_nop 0
	s_nop 0
	s_nop 0
	s_nop 0
	s_nop 0
	s_nop 0
	s_nop 0
	s_nop 0
	s_nop 0
	s_nop 0
	v_mov_b64_e32 v[0:1], 0
	v_mov_b64_e32 v[2:3], 0
	v_mov_b64_e32 v[4:5], 0
	v_mov_b64_e32 v[6:7], 0
	v_mov_b64_e32 v[8:9], 0
	v_mov_b64_e32 v[10:11], 0
	v_mov_b64_e32 v[12:13], 0
	v_mov_b64_e32 v[14:15], 0
	v_mov_b64_e32 v[16:17], 0
	v_mov_b64_e32 v[18:19], 0
	v_mov_b64_e32 v[20:21], 0
	v_mov_b64_e32 v[22:23], 0
	v_mov_b64_e32 v[24:25], 0
	v_mov_b64_e32 v[26:27], 0
	v_mov_b64_e32 v[28:29], 0
	v_mov_b64_e32 v[30:31], 0
	v_mov_b64_e32 v[32:33], 0
	v_mov_b64_e32 v[34:35], 0
	v_mov_b64_e32 v[36:37], 0
	v_mov_b64_e32 v[38:39], 0
	v_mov_b64_e32 v[40:41], 0
	v_mov_b64_e32 v[42:43], 0
	v_mov_b64_e32 v[44:45], 0
	v_mov_b64_e32 v[46:47], 0
	v_mov_b64_e32 v[48:49], 0
	v_mov_b64_e32 v[50:51], 0
	v_mov_b64_e32 v[52:53], 0
	v_mov_b64_e32 v[54:55], 0
	v_mov_b64_e32 v[56:57], 0
	v_mov_b64_e32 v[58:59], 0
	v_mov_b64_e32 v[60:61], 0
	v_mov_b64_e32 v[62:63], 0
	v_mov_b64_e32 v[64:65], 0
	v_mov_b64_e32 v[66:67], 0
	v_mov_b64_e32 v[68:69], 0
	v_mov_b64_e32 v[70:71], 0
	v_mov_b64_e32 v[72:73], 0
	v_mov_b64_e32 v[74:75], 0
	v_mov_b64_e32 v[76:77], 0
	v_mov_b64_e32 v[78:79], 0
	v_mov_b64_e32 v[80:81], 0
	v_mov_b64_e32 v[82:83], 0
	v_mov_b64_e32 v[84:85], 0
	v_mov_b64_e32 v[86:87], 0
	v_mov_b64_e32 v[88:89], 0
	v_mov_b64_e32 v[90:91], 0
	v_mov_b64_e32 v[92:93], 0
	v_mov_b64_e32 v[94:95], 0
	v_mov_b64_e32 v[96:97], 0
	v_mov_b64_e32 v[98:99], 0
	v_mov_b64_e32 v[100:101], 0
	v_mov_b64_e32 v[102:103], 0
	v_mov_b64_e32 v[104:105], 0
	v_mov_b64_e32 v[106:107], 0
	v_mov_b64_e32 v[108:109], 0
	v_mov_b64_e32 v[110:111], 0
	v_mov_b64_e32 v[112:113], 0
	v_mov_b64_e32 v[114:115], 0
	v_mov_b64_e32 v[116:117], 0
	v_mov_b64_e32 v[118:119], 0
	v_mov_b64_e32 v[120:121], 0
	v_mov_b64_e32 v[122:123], 0
	v_mov_b64_e32 v[124:125], 0
	v_mov_b64_e32 v[126:127], 0

.LBB0_1054:
	s_add_u32 s37, s16, 0x100
	s_addc_u32 s38, s17, 0
	s_mov_b32 s39, -2
	s_nop 0
	s_nop 0
	s_nop 0
	s_nop 0
	s_nop 0
	s_nop 0
	s_nop 0
	s_nop 0
	s_nop 0
	s_nop 0
	s_nop 0
	s_nop 0
	v_mov_b64_e32 v[0:1], 0
	v_mov_b64_e32 v[2:3], 0
	v_mov_b64_e32 v[4:5], 0
	v_mov_b64_e32 v[6:7], 0
	v_mov_b64_e32 v[8:9], 0
	v_mov_b64_e32 v[10:11], 0
	v_mov_b64_e32 v[12:13], 0
	v_mov_b64_e32 v[14:15], 0
	v_mov_b64_e32 v[16:17], 0
	v_mov_b64_e32 v[18:19], 0
	v_mov_b64_e32 v[20:21], 0
	v_mov_b64_e32 v[22:23], 0
	v_mov_b64_e32 v[24:25], 0
	v_mov_b64_e32 v[26:27], 0
	v_mov_b64_e32 v[28:29], 0
	v_mov_b64_e32 v[30:31], 0
	v_mov_b64_e32 v[32:33], 0
	v_mov_b64_e32 v[34:35], 0
	v_mov_b64_e32 v[36:37], 0
	v_mov_b64_e32 v[38:39], 0
	v_mov_b64_e32 v[40:41], 0
	v_mov_b64_e32 v[42:43], 0
	v_mov_b64_e32 v[44:45], 0
	v_mov_b64_e32 v[46:47], 0
	v_mov_b64_e32 v[48:49], 0
	v_mov_b64_e32 v[50:51], 0
	v_mov_b64_e32 v[52:53], 0
	v_mov_b64_e32 v[54:55], 0
	v_mov_b64_e32 v[56:57], 0
	v_mov_b64_e32 v[58:59], 0
	v_mov_b64_e32 v[60:61], 0
	v_mov_b64_e32 v[62:63], 0
	v_mov_b64_e32 v[64:65], 0
	v_mov_b64_e32 v[66:67], 0
	v_mov_b64_e32 v[68:69], 0
	v_mov_b64_e32 v[70:71], 0
	v_mov_b64_e32 v[72:73], 0
	v_mov_b64_e32 v[74:75], 0
	v_mov_b64_e32 v[76:77], 0
	v_mov_b64_e32 v[78:79], 0
	v_mov_b64_e32 v[80:81], 0
	v_mov_b64_e32 v[82:83], 0
	v_mov_b64_e32 v[84:85], 0
	v_mov_b64_e32 v[86:87], 0
	v_mov_b64_e32 v[88:89], 0
	v_mov_b64_e32 v[90:91], 0
	v_mov_b64_e32 v[92:93], 0
	v_mov_b64_e32 v[94:95], 0
	v_mov_b64_e32 v[96:97], 0
	v_mov_b64_e32 v[98:99], 0
	v_mov_b64_e32 v[100:101], 0
	v_mov_b64_e32 v[102:103], 0
	v_mov_b64_e32 v[104:105], 0
	v_mov_b64_e32 v[106:107], 0
	v_mov_b64_e32 v[108:109], 0
	v_mov_b64_e32 v[110:111], 0
	v_mov_b64_e32 v[112:113], 0
	v_mov_b64_e32 v[114:115], 0
	v_mov_b64_e32 v[116:117], 0
	v_mov_b64_e32 v[118:119], 0
	v_mov_b64_e32 v[120:121], 0
	v_mov_b64_e32 v[122:123], 0
	v_mov_b64_e32 v[124:125], 0
	v_mov_b64_e32 v[126:127], 0
